# V^T GEMM units remapped so each XCC shares 8 token tiles x 4 feature tiles (L2 reuse); barrier before the QK/VT phase made XCC-local
# speedup vs baseline: 1.0132x; 1.0034x over previous
; #define PG8_STAGE(bufoff, gbase, voff) do { _Pragma("unroll") for (int _i = 0; _i < 2; ++_i) \
;         __builtin_amdgcn_global_load_lds((const unsigned*)((const char*)(gbase) + (voff)[_i]), (LAS unsigned*)(lds + (bufoff) + ldsw + _i * 8192), 16, 0, 0); } while (0)
; #define PG8_BAR __builtin_amdgcn_s_barrier()
; template <class Epi, class Sched>
; __device__ __forceinline__ void gemm_phase(const int tid, LAS unsigned char* lds, const int lda, const int ldb, const int K, const Sched& S, const Epi& E) {
;     const int wid = __builtin_amdgcn_readfirstlane(tid >> 6), lane = tid & 63, wr = wid >> 2, wc = wid & 3, fr = lane & 15, fq = lane >> 4;
;     int nt = K / BK; asm volatile("" : "+s"(nt));
;     unsigned voffA[2], voffB[2];
; #pragma unroll
;     for (int i = 0; i < 2; ++i) { int R, C; stage_rc(tid * 16 + i * 8192, R, C); const int Rb = (R & ~31) + perm32(R & 31);
;         voffA[i] = (unsigned)(R * lda + C) * 2u; voffB[i] = (unsigned)(Rb * ldb + C) * 2u; }
;     const size_t kstep = (size_t)(BK * 2);
;     const size_t hstepA = (size_t)HALF * lda * 2, hstepB = (size_t)HALF * ldb * 2;
;     const unsigned ldsw = (unsigned)wid * 1024u;
;     const int aoff = lds_byte(wr * 64 + fr, fq * 8), boff = lds_byte(wc * 32 + fr, fq * 8);
;     ...
;     Unit cur, nxt; int ui = 0;
;     if (!S.next(0, cur)) return;
;     f32x4 acc[2][2][4][2];
;     float es0 = 0.f, es1 = 0.f;
;     E.pre(cur, wr, wc, fr, fq, es0, es1);
;     E.init(acc, cur, wr, wc, fr, fq);
;     bf16x8 At[4][2], B0[2][2], B1[2][2];
;     const char* cA = cur.a; const char* cB = cur.b;
;     PG8_STAGE(PG8_SB(0, 0), cB, voffB); PG8_STAGE(PG8_SB(0, 1), cB + hstepB, voffB); PG8_STAGE(PG8_SA(0, 0), cA, voffA); PG8_STAGE(PG8_SA(0, 1), cA + hstepA, voffA);
;     if (wr == 1) PG8_BAR;
;     __device__ __forceinline__ bool next(int i, Unit& u) const {
;         const int L = i * G + c; if (L >= 256) return false;
;         u.pm = L & 3; u.pn = L >> 2; u.g = 1; u.half = 0; u.sub = 0;
;         u.a = Wv + (size_t)u.pm * BM * D * 2; u.b = HBp + (size_t)u.pn * BM * D * 2;
;         return true;
.LBB0_205:
	s_waitcnt vmcnt(0)
	v_mov_b32_e32 v0, v203
	s_mov_b32 s13, 16
	v_readfirstlane_b32 s2, v0
	s_cmpk_gt_i32 s28, 0xff
	s_cbranch_scc1 .LBB0_223
	s_waitcnt lgkmcnt(0)
	v_lshlrev_b32_e32 v1, 4, v0
	v_add_u32_e32 v2, 0x2000, v1
	v_ashrrev_i32_e32 v3, 31, v2
	v_lshrrev_b32_e32 v3, 22, v3
	v_add_u32_e32 v3, v2, v3
	v_ashrrev_i32_e32 v40, 10, v3
	v_mul_i32_i24_e32 v3, 0x400, v40
	v_sub_u32_e32 v2, v2, v3
	v_lshrrev_b32_e32 v3, 4, v2
	v_bitop3_b32 v2, v3, v2, 32 bitop3:0x6c
	s_add_u32 s29, s10, 0x9500000
	v_ashrrev_i32_e32 v3, 31, v2
	s_addc_u32 s31, s11, 0
	s_ashr_i32 s4, s2, 6
	v_lshrrev_b32_e32 v3, 26, v3
	s_lshl_b32 s60, s4, 10
	s_lshl_b32 s4, s4, 5
	s_and_b32 s50, s28, 7
	s_lshl_b32 s50, s50, 3
	s_lshr_b32 s51, s28, 5
	s_add_i32 s50, s50, s51
	v_add_u32_e32 v3, v2, v3
	v_lshlrev_b32_e32 v4, 3, v40
	s_and_b32 s61, s4, 0x60
	s_bfe_u32 s4, s28, 0x20003
	s_ashr_i32 s51, s50, 31
	v_ashrrev_i32_e32 v42, 6, v3
	v_and_b32_e32 v4, -16, v4
	s_ashr_i32 s3, s2, 8
	s_lshl_b32 s14, s4, 19
	s_lshl_b64 s[22:23], s[50:51], 19
	v_add_u32_e32 v4, v42, v4
	s_add_u32 s54, s29, s14
	v_and_b32_e32 v5, 3, v42
	s_mov_b32 s14, 0x1fffe0
	v_lshrrev_b32_e32 v6, 2, v4
	v_lshlrev_b32_e32 v7, 1, v4
	v_and_b32_e32 v3, 0xc0, v3
	v_and_or_b32 v5, v4, s14, v5
	v_and_b32_e32 v6, 4, v6
	v_and_b32_e32 v7, 24, v7
	v_sub_u32_e32 v2, v2, v3
	v_or3_b32 v5, v5, v6, v7
	v_lshlrev_b32_e32 v6, 5, v40
	v_ashrrev_i16_sdwa v2, v188, sext(v2) dst_sel:DWORD dst_unused:UNUSED_PAD src0_sel:DWORD src1_sel:BYTE_0
	v_and_b32_e32 v6, 32, v6
	v_bfe_i32 v43, v2, 0, 16
	v_add_lshl_u32 v2, v6, v43, 1
	v_lshl_add_u32 v128, v5, 11, v2
	v_lshl_add_u32 v130, v4, 11, v2
	v_bfe_i32 v2, v0, 27, 1
	v_lshrrev_b32_e32 v2, 22, v2
	v_add_u32_e32 v2, v1, v2
	v_and_b32_e32 v2, 0xfffffc00, v2
	v_sub_u32_e32 v1, v1, v2
	v_lshrrev_b32_e32 v2, 4, v1
	v_ashrrev_i32_e32 v3, 31, v0
	v_bitop3_b32 v1, v2, v1, 32 bitop3:0x6c
	v_lshrrev_b32_e32 v3, 26, v3
	v_and_b32_e32 v148, 15, v0
	v_bfe_u32 v41, v0, 4, 2
	v_ashrrev_i32_e32 v2, 31, v1
	v_add_u32_e32 v0, v0, v3
	v_lshrrev_b32_e32 v2, 26, v2
	v_ashrrev_i32_e32 v45, 6, v0
	v_add_u32_e32 v2, v1, v2
	v_lshlrev_b32_e32 v0, 3, v45
	v_ashrrev_i32_e32 v44, 6, v2
	v_and_b32_e32 v0, -16, v0
	v_add_u32_e32 v0, v44, v0
	v_and_b32_e32 v3, 3, v44
	v_lshrrev_b32_e32 v4, 2, v0
	v_lshlrev_b32_e32 v5, 1, v0
	v_and_b32_e32 v2, 0xc0, v2
	v_and_or_b32 v3, v0, s14, v3
	v_and_b32_e32 v4, 4, v4
	v_and_b32_e32 v5, 24, v5
	v_sub_u32_e32 v1, v1, v2
	v_or3_b32 v3, v3, v4, v5
	v_lshlrev_b32_e32 v4, 5, v45
	v_ashrrev_i16_sdwa v1, v188, sext(v1) dst_sel:DWORD dst_unused:UNUSED_PAD src0_sel:DWORD src1_sel:BYTE_0
	v_and_b32_e32 v4, 32, v4
	v_bfe_i32 v46, v1, 0, 16
	v_add_lshl_u32 v1, v4, v46, 1
	v_lshl_add_u32 v134, v0, 11, v1
	v_mov_b32_e32 v0, v148
	v_lshlrev_b32_e32 v149, 4, v41
	v_lshl_add_u32 v132, v3, 11, v1
	v_add_u32_e32 v0, v0, v149
	v_lshlrev_b32_e32 v1, 2, v0
	v_and_b32_e32 v1, 0xffffff80, v1
	v_lshl_add_u32 v1, s50, 8, v1
	v_and_b32_e32 v0, 31, v0
	s_addc_u32 s55, s31, 0
	v_or3_b32 v0, v1, v0, s61
	s_add_u32 s56, s90, s22
	v_ashrrev_i32_e32 v1, 31, v0
	s_addc_u32 s57, s91, s23
	v_lshlrev_b64 v[0:1], 7, v[0:1]
	s_add_i32 s51, s60, 0
	v_lshl_add_u64 v[16:17], s[94:95], 0, v[0:1]
	s_add_i32 m0, s51, 0x10000
	global_load_dwordx4 v[12:15], v[16:17], off offset:48
	global_load_dwordx4 v[20:23], v[16:17], off offset:32
	global_load_dwordx4 v[24:27], v[16:17], off offset:16
	global_load_dwordx4 v[28:31], v[16:17], off
	global_load_dwordx4 v[0:3], v[16:17], off offset:112
	global_load_dwordx4 v[4:7], v[16:17], off offset:96
	global_load_dwordx4 v[8:11], v[16:17], off offset:80
	s_nop 0
	global_load_dwordx4 v[16:19], v[16:17], off offset:64
	v_mov_b32_e32 v133, v169
	global_load_lds_dwordx4 v132, s[56:57]
	s_add_i32 m0, s51, 0x12000
	s_add_u32 s22, s56, 0x40000
	global_load_lds_dwordx4 v128, s[56:57]
	s_addc_u32 s23, s57, 0
	s_add_i32 m0, s51, 0x14000
	s_add_i32 s62, s51, 0x2000
	global_load_lds_dwordx4 v132, s[22:23]
	s_add_i32 m0, s51, 0x16000
	v_mov_b32_e32 v129, v169
	global_load_lds_dwordx4 v128, s[22:23]
	s_mov_b32 m0, s51
	s_add_u32 s22, s54, 0x40000
	global_load_lds_dwordx4 v134, s[54:55]
	s_mov_b32 m0, s62
	s_addc_u32 s23, s55, 0
	s_add_i32 s63, s51, 0x4000
	global_load_lds_dwordx4 v130, s[54:55]
	s_mov_b32 m0, s63
	s_add_i32 s64, s51, 0x6000
	global_load_lds_dwordx4 v134, s[22:23]
	s_mov_b32 m0, s64
	v_mov_b32_e32 v135, v169
	global_load_lds_dwordx4 v130, s[22:23]
	v_mov_b32_e32 v131, v169
	s_cmp_eq_u32 s3, 1
	v_lshl_add_u64 v[38:39], s[56:57], 0, v[132:133]
	v_lshl_add_u64 v[36:37], s[56:57], 0, v[128:129]
	v_lshl_add_u64 v[32:33], s[54:55], 0, v[134:135]
	s_cselect_b64 s[38:39], -1, 0
	s_cmp_lg_u32 s3, 1
	v_lshl_add_u64 v[34:35], s[54:55], 0, v[130:131]
	s_cbranch_scc1 .LBB0_208
	s_barrier

; __global__ void __launch_bounds__(NTHR, 2) fwd_kernel(Args args) {
;     ...
;     for (int ph = args.ph_lo; ph < args.ph_hi; ++ph) {
;     ...
;         if (ph + 1 < args.ph_hi) {
;             int tid2 = threadIdx.x; asm volatile("" : "+v"(tid2));
;             xcd_barrier(xbar, tid2); if ((MK_REP >> 18) & 1u) xcd_barrier(xbar, tid2);
;         }
.LBB0_1003:
	s_mov_b32 s2, 0xb0689a84
	s_movk_i32 s3, 0xa1
	s_lshr_b64 s[2:3], s[2:3], s68
	s_and_b32 s2, s2, 1
	s_and_b32 s101, s2, s100
	s_add_i32 s68, s68, 1
	s_cmp_ge_i32 s68, s69
	s_cselect_b64 s[2:3], -1, 0
	s_or_b64 s[2:3], s[36:37], s[2:3]
	v_readlane_b32 s26, v254, 58
	s_andn2_b64 vcc, exec, s[2:3]
	v_readlane_b32 s27, v254, 59
	s_cbranch_vccnz .LBB0_1004
	s_getpc_b64 s[98:99]
